# gdn chunk tail: the four QB read-modify-write loads issued before the PN MFMA stage into AGPRs (one wait instead of four round trips)
# speedup vs baseline: 1.2412x; 1.0033x over previous
; __device__ __forceinline__ float bflo(unsigned u) { return __uint_as_float(u << 16); }
; __device__ __forceinline__ float bfhi(unsigned u) { return __uint_as_float(u & 0xffff0000u); }
; __device__ __forceinline__ void gdn_chunk_item(const Params& p, int item, char* smem) {
;     ...
; #pragma unroll
;     for (int q = 0; q < 4; q++) {
;       const int idx = tid + 256 * q, row = idx >> 4, c8 = idx & 15;
;       *(uint4*)&Oo[(size_t)(tok0 + row) * 512 + h * 128 + c8 * 8] = *(const uint4*)&O0T[row * 136 + c8 * 8];
;       const uint4 a4 = *(const uint4*)&QB[row * 128 + c8 * 8];
;       const uint4 w4 = *(const uint4*)&QWT[row * 136 + c8 * 8];
;       *(uint4*)&QB[row * 128 + c8 * 8] = make_uint4(pack2(bflo(a4.x) - bflo(w4.x), bfhi(a4.x) - bfhi(w4.x)), pack2(bflo(a4.y) - bflo(w4.y), bfhi(a4.y) - bfhi(w4.y)),
;                                                      pack2(bflo(a4.z) - bflo(w4.z), bfhi(a4.z) - bfhi(w4.z)), pack2(bflo(a4.w) - bflo(w4.w), bfhi(a4.w) - bfhi(w4.w)));
;     }
; #pragma unroll
;     for (int q = 0; q < 8; q++) {
;       const int idx = tid + 256 * q, row = idx >> 4, c8 = idx & 15;
;       *(uint4*)&PN[row * 128 + c8 * 8] = *(const uint4*)&PNT[row * 136 + c8 * 8];
;     }
.LBB0_797:
	s_or_b64 exec, exec, s[6:7]
	s_ashr_i32 s85, s84, 31
	v_accvgpr_read_b32 v12, a96
	s_lshl_b64 s[0:1], s[84:85], 15
	s_waitcnt lgkmcnt(0)
	s_barrier
	v_accvgpr_read_b32 v2, a126
	ds_read_b128 v[12:15], v12
	s_add_u32 s0, s34, s0
	v_or_b32_e32 v2, s55, v2
	s_addc_u32 s1, s35, s1
	s_lshl_b32 s56, s72, 1
	v_ashrrev_i32_e32 v3, 31, v2
	v_lshl_add_u64 v[0:1], v[42:43], 0, s[56:57]
	v_lshlrev_b64 v[2:3], 10, v[2:3]
	v_lshl_add_u64 v[2:3], v[0:1], 0, v[2:3]
	s_waitcnt lgkmcnt(0)
	global_store_dwordx4 v[2:3], v[12:15], off
	s_nop 1
	v_accvgpr_read_b32 v12, a196
	v_accvgpr_read_b32 v13, a197
	v_accvgpr_read_b32 v14, a198
	v_accvgpr_read_b32 v15, a199
	v_accvgpr_read_b32 v2, a97
	ds_read_b128 v[16:19], v2
	s_add_i32 s84, s84, s82
	s_cmpk_lt_i32 s84, 0x400
	s_waitcnt lgkmcnt(0)
	v_lshlrev_b32_e32 v20, 16, v16
	v_and_b32_e32 v21, 0xffff0000, v16
	v_lshlrev_b32_e32 v16, 16, v17
	v_and_b32_e32 v17, 0xffff0000, v17
	v_lshlrev_b32_e32 v2, 16, v12
	v_and_b32_e32 v3, 0xffff0000, v12
	v_pk_add_f32 v[2:3], v[2:3], v[20:21] neg_lo:[0,1] neg_hi:[0,1]
	s_nop 0
	v_cvt_pk_bf16_f32 v12, v2, v3
	v_lshlrev_b32_e32 v2, 16, v13
	v_and_b32_e32 v3, 0xffff0000, v13
	v_pk_add_f32 v[2:3], v[2:3], v[16:17] neg_lo:[0,1] neg_hi:[0,1]
	v_lshlrev_b32_e32 v16, 16, v18
	v_cvt_pk_bf16_f32 v13, v2, v3
	v_lshlrev_b32_e32 v2, 16, v14
	v_and_b32_e32 v3, 0xffff0000, v14
	v_and_b32_e32 v17, 0xffff0000, v18
	v_pk_add_f32 v[2:3], v[2:3], v[16:17] neg_lo:[0,1] neg_hi:[0,1]
	v_lshlrev_b32_e32 v16, 16, v19
	v_cvt_pk_bf16_f32 v14, v2, v3
	v_lshlrev_b32_e32 v2, 16, v15
	v_and_b32_e32 v3, 0xffff0000, v15
	v_and_b32_e32 v17, 0xffff0000, v19
	v_pk_add_f32 v[2:3], v[2:3], v[16:17] neg_lo:[0,1] neg_hi:[0,1]
	s_nop 0
	v_cvt_pk_bf16_f32 v15, v2, v3
	global_store_dwordx4 v[10:11], v[12:15], off
	v_accvgpr_read_b32 v10, a98
	v_accvgpr_read_b32 v2, a135
	ds_read_b128 v[10:13], v10
	v_add_u32_e32 v2, s55, v2
	v_ashrrev_i32_e32 v3, 31, v2
	v_lshlrev_b64 v[2:3], 10, v[2:3]
	v_lshl_add_u64 v[2:3], v[0:1], 0, v[2:3]
	s_waitcnt lgkmcnt(0)
	global_store_dwordx4 v[2:3], v[10:13], off
	s_nop 1
	v_accvgpr_read_b32 v10, a200
	v_accvgpr_read_b32 v11, a201
	v_accvgpr_read_b32 v12, a202
	v_accvgpr_read_b32 v13, a203
	v_accvgpr_read_b32 v2, a99
	ds_read_b128 v[14:17], v2
	s_waitcnt lgkmcnt(0)
	v_lshlrev_b32_e32 v18, 16, v14
	v_and_b32_e32 v19, 0xffff0000, v14
	v_lshlrev_b32_e32 v14, 16, v15
	v_and_b32_e32 v15, 0xffff0000, v15
	v_lshlrev_b32_e32 v2, 16, v10
	v_and_b32_e32 v3, 0xffff0000, v10
	v_pk_add_f32 v[2:3], v[2:3], v[18:19] neg_lo:[0,1] neg_hi:[0,1]
	s_nop 0
	v_cvt_pk_bf16_f32 v10, v2, v3
	v_lshlrev_b32_e32 v2, 16, v11
	v_and_b32_e32 v3, 0xffff0000, v11
	v_pk_add_f32 v[2:3], v[2:3], v[14:15] neg_lo:[0,1] neg_hi:[0,1]
	v_lshlrev_b32_e32 v14, 16, v16
	v_cvt_pk_bf16_f32 v11, v2, v3
	v_lshlrev_b32_e32 v2, 16, v12
	v_and_b32_e32 v3, 0xffff0000, v12
	v_and_b32_e32 v15, 0xffff0000, v16
	v_pk_add_f32 v[2:3], v[2:3], v[14:15] neg_lo:[0,1] neg_hi:[0,1]
	v_lshlrev_b32_e32 v14, 16, v17
	v_cvt_pk_bf16_f32 v12, v2, v3
	v_lshlrev_b32_e32 v2, 16, v13
	v_and_b32_e32 v3, 0xffff0000, v13
	v_and_b32_e32 v15, 0xffff0000, v17
	v_pk_add_f32 v[2:3], v[2:3], v[14:15] neg_lo:[0,1] neg_hi:[0,1]
	s_nop 0
	v_cvt_pk_bf16_f32 v13, v2, v3
	global_store_dwordx4 v[8:9], v[10:13], off
	v_accvgpr_read_b32 v8, a100
	v_accvgpr_read_b32 v2, a133
	ds_read_b128 v[8:11], v8
	v_add_u32_e32 v2, s55, v2
	v_ashrrev_i32_e32 v3, 31, v2
	v_lshlrev_b64 v[2:3], 10, v[2:3]
	v_lshl_add_u64 v[2:3], v[0:1], 0, v[2:3]
	s_waitcnt lgkmcnt(0)
	global_store_dwordx4 v[2:3], v[8:11], off
	s_nop 1
	v_accvgpr_read_b32 v8, a204
	v_accvgpr_read_b32 v9, a205
	v_accvgpr_read_b32 v10, a206
	v_accvgpr_read_b32 v11, a207
	v_accvgpr_read_b32 v2, a101
	ds_read_b128 v[12:15], v2
	s_waitcnt lgkmcnt(0)
	v_lshlrev_b32_e32 v16, 16, v12
	v_and_b32_e32 v17, 0xffff0000, v12
	v_lshlrev_b32_e32 v12, 16, v13
	v_and_b32_e32 v13, 0xffff0000, v13
	v_lshlrev_b32_e32 v2, 16, v8
	v_and_b32_e32 v3, 0xffff0000, v8
	v_pk_add_f32 v[2:3], v[2:3], v[16:17] neg_lo:[0,1] neg_hi:[0,1]
	s_nop 0
	v_cvt_pk_bf16_f32 v8, v2, v3
	v_lshlrev_b32_e32 v2, 16, v9
	v_and_b32_e32 v3, 0xffff0000, v9
	v_pk_add_f32 v[2:3], v[2:3], v[12:13] neg_lo:[0,1] neg_hi:[0,1]
	v_lshlrev_b32_e32 v12, 16, v14
	v_cvt_pk_bf16_f32 v9, v2, v3
	v_lshlrev_b32_e32 v2, 16, v10
	v_and_b32_e32 v3, 0xffff0000, v10
	v_and_b32_e32 v13, 0xffff0000, v14
	v_pk_add_f32 v[2:3], v[2:3], v[12:13] neg_lo:[0,1] neg_hi:[0,1]
	v_lshlrev_b32_e32 v12, 16, v15
	v_cvt_pk_bf16_f32 v10, v2, v3
	v_lshlrev_b32_e32 v2, 16, v11
	v_and_b32_e32 v3, 0xffff0000, v11
	v_and_b32_e32 v13, 0xffff0000, v15
	v_pk_add_f32 v[2:3], v[2:3], v[12:13] neg_lo:[0,1] neg_hi:[0,1]
	s_nop 0
	v_cvt_pk_bf16_f32 v11, v2, v3
	v_add_u32_e32 v2, s55, v236
	v_ashrrev_i32_e32 v3, 31, v2
	v_lshlrev_b64 v[2:3], 10, v[2:3]
	global_store_dwordx4 v[6:7], v[8:11], off
	v_lshl_add_u64 v[6:7], v[0:1], 0, v[2:3]
	v_accvgpr_read_b32 v0, a102
	ds_read_b128 v[0:3], v0
	s_waitcnt lgkmcnt(0)
	global_store_dwordx4 v[6:7], v[0:3], off
	s_nop 1
	v_accvgpr_read_b32 v0, a208
	v_accvgpr_read_b32 v1, a209
	v_accvgpr_read_b32 v2, a210
	v_accvgpr_read_b32 v3, a211
	v_accvgpr_read_b32 v6, a103
	ds_read_b128 v[6:9], v6
	s_waitcnt lgkmcnt(0)
	v_lshlrev_b32_e32 v12, 16, v6
	v_and_b32_e32 v13, 0xffff0000, v6
	v_lshlrev_b32_e32 v6, 16, v7
	v_and_b32_e32 v7, 0xffff0000, v7
	v_lshlrev_b32_e32 v10, 16, v0
	v_and_b32_e32 v11, 0xffff0000, v0
	v_pk_add_f32 v[10:11], v[10:11], v[12:13] neg_lo:[0,1] neg_hi:[0,1]
	s_nop 0
	v_cvt_pk_bf16_f32 v0, v10, v11
	v_lshlrev_b32_e32 v10, 16, v1
	v_and_b32_e32 v11, 0xffff0000, v1
	v_pk_add_f32 v[6:7], v[10:11], v[6:7] neg_lo:[0,1] neg_hi:[0,1]
	v_lshlrev_b32_e32 v10, 16, v8
	v_cvt_pk_bf16_f32 v1, v6, v7
	v_lshlrev_b32_e32 v6, 16, v2
	v_and_b32_e32 v7, 0xffff0000, v2
	v_and_b32_e32 v11, 0xffff0000, v8
	v_pk_add_f32 v[6:7], v[6:7], v[10:11] neg_lo:[0,1] neg_hi:[0,1]
	v_lshlrev_b32_e32 v8, 16, v9
	v_cvt_pk_bf16_f32 v2, v6, v7
	v_lshlrev_b32_e32 v6, 16, v3
	v_and_b32_e32 v7, 0xffff0000, v3
	v_and_b32_e32 v9, 0xffff0000, v9
	v_pk_add_f32 v[6:7], v[6:7], v[8:9] neg_lo:[0,1] neg_hi:[0,1]
	s_nop 0
	v_cvt_pk_bf16_f32 v3, v6, v7
	global_store_dwordx4 v[4:5], v[0:3], off
	ds_read_b128 v[0:3], v242
	s_waitcnt lgkmcnt(0)
	global_store_dwordx4 v52, v[0:3], s[0:1]
	ds_read_b128 v[0:3], v243
	s_waitcnt lgkmcnt(0)
	global_store_dwordx4 v46, v[0:3], s[0:1]
	ds_read_b128 v[0:3], v244
	s_waitcnt lgkmcnt(0)
	global_store_dwordx4 v48, v[0:3], s[0:1]
	ds_read_b128 v[0:3], v245
	s_waitcnt lgkmcnt(0)
	global_store_dwordx4 v50, v[0:3], s[0:1]
	ds_read_b128 v[0:3], v246
	s_waitcnt lgkmcnt(0)
	global_store_dwordx4 v230, v[0:3], s[0:1]
	ds_read_b128 v[0:3], v247
	s_waitcnt lgkmcnt(0)
	global_store_dwordx4 v231, v[0:3], s[0:1]
	ds_read_b128 v[0:3], v248
	s_waitcnt lgkmcnt(0)
	global_store_dwordx4 v232, v[0:3], s[0:1]
	ds_read_b128 v[0:3], v249
	s_waitcnt lgkmcnt(0)
	global_store_dwordx4 v233, v[0:3], s[0:1]
	s_cbranch_scc0 .LBB0_901

; __device__ __forceinline__ u16 f2bf(float f) { return (u16)(pack2(f, f) & 0xffffu); }
; __device__ __forceinline__ int rowmap(int e, int lane) { return (e & 3) + 8 * (e >> 2) + 4 * (lane >> 5); }
; __device__ __forceinline__ void gdn_chunk_item(const Params& p, int item, char* smem) {
;     ...
;     const int mi = w & 1, ni0 = (w >> 1) * 2;
; #pragma unroll
;     for (int jj = 0; jj < 2; jj++) {
;       const int ni = ni0 + jj;
;       f32x16 o0 = zero16(), qw = zero16();
; #pragma unroll
;       for (int ks = 0; ks < 4; ks++) {
;         bf16x8 a = *(const bf16x8*)&QKs[(mi * 32 + r) * 72 + ks * 16 + hh];
;         bf16x8 bu = *(const bf16x8*)&U0T[(ni * 32 + r) * 72 + ks * 16 + hh];
;         bf16x8 bw = *(const bf16x8*)&WTl[(ni * 32 + r) * 72 + ks * 16 + hh];
;         o0 = mfma16(a, bu, o0); qw = mfma16(a, bw, qw);
;       }
;       const int col = ni * 32 + r;
; #pragma unroll
;       for (int e = 0; e < 16; e++) {
;         const int t = mi * 32 + rowmap(e, lane);
;         O0T[t * 136 + col] = f2bf(o0[e]);
;         QWT[t * 136 + col] = f2bf(qw[e]);
;       }
;     }
.LBB0_899:
	s_or_b64 exec, exec, s[36:37]
	s_waitcnt lgkmcnt(0)
	s_barrier
	ds_read_b128 v[0:3], v212 offset:55296
	ds_read_b128 v[12:15], v213 offset:36864
	v_accvgpr_read_b32 v29, a32
	s_waitcnt lgkmcnt(0)
	v_mfma_f32_32x32x16_bf16 a[16:31], v[0:3], v[12:15], 0
	ds_read_b128 v[12:15], v213 offset:18432
	s_waitcnt lgkmcnt(0)
	v_mfma_f32_32x32x16_bf16 a[0:15], v[0:3], v[12:15], 0
	ds_read_b128 v[12:15], v212 offset:55328
	ds_read_b128 v[16:19], v213 offset:36896
	s_waitcnt lgkmcnt(0)
	v_mfma_f32_32x32x16_bf16 a[16:31], v[12:15], v[16:19], a[16:31]
	ds_read_b128 v[16:19], v213 offset:18464
	s_waitcnt lgkmcnt(0)
	v_mfma_f32_32x32x16_bf16 a[0:15], v[12:15], v[16:19], a[0:15]
	ds_read_b128 v[16:19], v212 offset:55360
	ds_read_b128 v[20:23], v213 offset:36928
	s_waitcnt lgkmcnt(0)
	v_mfma_f32_32x32x16_bf16 a[16:31], v[16:19], v[20:23], a[16:31]
	ds_read_b128 v[20:23], v213 offset:18496
	s_waitcnt lgkmcnt(0)
	v_mfma_f32_32x32x16_bf16 a[0:15], v[16:19], v[20:23], a[0:15]
	ds_read_b128 v[20:23], v212 offset:55392
	ds_read_b128 v[24:27], v213 offset:36960
	s_waitcnt lgkmcnt(0)
	v_mfma_f32_32x32x16_bf16 a[16:31], v[20:23], v[24:27], a[16:31]
	ds_read_b128 v[24:27], v213 offset:18528
	s_waitcnt lgkmcnt(0)
	v_mfma_f32_32x32x16_bf16 a[0:15], v[20:23], v[24:27], a[0:15]
	v_accvgpr_read_b32 v25, a33
	s_nop 7
	v_accvgpr_read_b32 v28, a16
	v_cvt_pk_bf16_f32 v28, v28, s0
	ds_write_b16 v29, v28
	v_accvgpr_read_b32 v24, a0
	v_cvt_pk_bf16_f32 v24, v24, s0
	ds_write_b16 v25, v24
	v_accvgpr_read_b32 v24, a17
	v_cvt_pk_bf16_f32 v24, v24, s0
	v_accvgpr_read_b32 v25, a34
	ds_write_b16 v25, v24
	v_accvgpr_read_b32 v24, a1
	v_cvt_pk_bf16_f32 v24, v24, s0
	v_accvgpr_read_b32 v25, a35
	ds_write_b16 v25, v24
	v_accvgpr_read_b32 v24, a18
	v_cvt_pk_bf16_f32 v24, v24, s0
	v_accvgpr_read_b32 v25, a36
	ds_write_b16 v25, v24
	v_accvgpr_read_b32 v24, a2
	v_cvt_pk_bf16_f32 v24, v24, s0
	v_accvgpr_read_b32 v25, a37
	ds_write_b16 v25, v24
	v_accvgpr_read_b32 v24, a19
	v_cvt_pk_bf16_f32 v24, v24, s0
	v_accvgpr_read_b32 v25, a38
	ds_write_b16 v25, v24
	v_accvgpr_read_b32 v24, a3
	v_cvt_pk_bf16_f32 v24, v24, s0
	v_accvgpr_read_b32 v25, a39
	ds_write_b16 v25, v24
	v_accvgpr_read_b32 v24, a20
	v_cvt_pk_bf16_f32 v24, v24, s0
	v_accvgpr_read_b32 v25, a40
	ds_write_b16 v25, v24
	v_accvgpr_read_b32 v24, a4
	v_cvt_pk_bf16_f32 v24, v24, s0
	v_accvgpr_read_b32 v25, a41
	ds_write_b16 v25, v24
	v_accvgpr_read_b32 v24, a21
	v_cvt_pk_bf16_f32 v24, v24, s0
	v_accvgpr_read_b32 v25, a42
	ds_write_b16 v25, v24
	v_accvgpr_read_b32 v24, a5
	v_cvt_pk_bf16_f32 v24, v24, s0
	v_accvgpr_read_b32 v25, a43
	ds_write_b16 v25, v24
	v_accvgpr_read_b32 v24, a22
	v_cvt_pk_bf16_f32 v24, v24, s0
	v_accvgpr_read_b32 v25, a44
	ds_write_b16 v25, v24
	v_accvgpr_read_b32 v24, a6
	v_cvt_pk_bf16_f32 v24, v24, s0
	v_accvgpr_read_b32 v25, a45
	ds_write_b16 v25, v24
	v_accvgpr_read_b32 v24, a23
	v_cvt_pk_bf16_f32 v24, v24, s0
	v_accvgpr_read_b32 v25, a46
	ds_write_b16 v25, v24
	v_accvgpr_read_b32 v24, a7
	v_cvt_pk_bf16_f32 v24, v24, s0
	v_accvgpr_read_b32 v25, a47
	ds_write_b16 v25, v24
	v_accvgpr_read_b32 v24, a24
	v_cvt_pk_bf16_f32 v24, v24, s0
	v_accvgpr_read_b32 v25, a48
	ds_write_b16 v25, v24
	v_accvgpr_read_b32 v24, a8
	v_cvt_pk_bf16_f32 v24, v24, s0
	v_accvgpr_read_b32 v25, a49
	ds_write_b16 v25, v24
	v_accvgpr_read_b32 v24, a25
	v_cvt_pk_bf16_f32 v24, v24, s0
	v_accvgpr_read_b32 v25, a50
	ds_write_b16 v25, v24
	v_accvgpr_read_b32 v24, a9
	v_cvt_pk_bf16_f32 v24, v24, s0
	v_accvgpr_read_b32 v25, a51
	ds_write_b16 v25, v24
	v_accvgpr_read_b32 v24, a26
	v_cvt_pk_bf16_f32 v24, v24, s0
	v_accvgpr_read_b32 v25, a52
	ds_write_b16 v25, v24
	v_accvgpr_read_b32 v24, a10
	v_cvt_pk_bf16_f32 v24, v24, s0
	v_accvgpr_read_b32 v25, a53
	ds_write_b16 v25, v24
	v_accvgpr_read_b32 v24, a27
	v_cvt_pk_bf16_f32 v24, v24, s0
	v_accvgpr_read_b32 v25, a54
	ds_write_b16 v25, v24
	v_accvgpr_read_b32 v24, a11
	v_cvt_pk_bf16_f32 v24, v24, s0
	v_accvgpr_read_b32 v25, a55
	ds_write_b16 v25, v24
	v_accvgpr_read_b32 v24, a28
	v_cvt_pk_bf16_f32 v24, v24, s0
	v_accvgpr_read_b32 v25, a56
	ds_write_b16 v25, v24
	v_accvgpr_read_b32 v24, a12
	v_cvt_pk_bf16_f32 v24, v24, s0
	v_accvgpr_read_b32 v25, a57
	ds_write_b16 v25, v24
	v_accvgpr_read_b32 v24, a29
	v_cvt_pk_bf16_f32 v24, v24, s0
	v_accvgpr_read_b32 v25, a58
	ds_write_b16 v25, v24
	v_accvgpr_read_b32 v24, a13
	v_cvt_pk_bf16_f32 v24, v24, s0
	v_accvgpr_read_b32 v25, a59
	ds_write_b16 v25, v24
	v_accvgpr_read_b32 v24, a30
	v_cvt_pk_bf16_f32 v24, v24, s0
	v_accvgpr_read_b32 v25, a60
	ds_write_b16 v25, v24
	v_accvgpr_read_b32 v24, a14
	v_cvt_pk_bf16_f32 v24, v24, s0
	v_accvgpr_read_b32 v25, a61
	ds_write_b16 v25, v24
	v_accvgpr_read_b32 v24, a31
	v_cvt_pk_bf16_f32 v24, v24, s0
	v_accvgpr_read_b32 v25, a62
	ds_write_b16 v25, v24
	v_accvgpr_read_b32 v24, a15
	v_cvt_pk_bf16_f32 v24, v24, s0
	v_accvgpr_read_b32 v25, a63
	ds_write_b16 v25, v24
	ds_read_b128 v[24:27], v252 offset:36864
	s_waitcnt lgkmcnt(0)
	v_mfma_f32_32x32x16_bf16 a[16:31], v[0:3], v[24:27], 0
	ds_read_b128 v[24:27], v252 offset:18432
	s_waitcnt lgkmcnt(0)
	v_mfma_f32_32x32x16_bf16 a[0:15], v[0:3], v[24:27], 0
	ds_read_b128 v[0:3], v252 offset:36896
	s_waitcnt lgkmcnt(0)
	v_mfma_f32_32x32x16_bf16 a[16:31], v[12:15], v[0:3], a[16:31]
	ds_read_b128 v[0:3], v252 offset:18464
	s_waitcnt lgkmcnt(0)
	v_mfma_f32_32x32x16_bf16 a[0:15], v[12:15], v[0:3], a[0:15]
	ds_read_b128 v[0:3], v252 offset:36928
	s_waitcnt lgkmcnt(0)
	v_mfma_f32_32x32x16_bf16 a[16:31], v[16:19], v[0:3], a[16:31]
	ds_read_b128 v[0:3], v252 offset:18496
	s_waitcnt lgkmcnt(0)
	v_mfma_f32_32x32x16_bf16 a[0:15], v[16:19], v[0:3], a[0:15]
	ds_read_b128 v[0:3], v252 offset:36960
	s_waitcnt lgkmcnt(0)
; __device__ __forceinline__ u16 f2bf(float f) { return (u16)(pack2(f, f) & 0xffffu); }
; __device__ __forceinline__ int rowmap(int e, int lane) { return (e & 3) + 8 * (e >> 2) + 4 * (lane >> 5); }
; __device__ __forceinline__ void gdn_chunk_item(const Params& p, int item, char* smem) {
;     ...
;       for (int e = 0; e < 16; e++) {
;         const int t = mi * 32 + rowmap(e, lane);
;         O0T[t * 136 + col] = f2bf(o0[e]);
;         QWT[t * 136 + col] = f2bf(qw[e]);
;       }
;     }
; #pragma unroll
;     for (int ni = 0; ni < 4; ni++) {
;       f32x16 pn = zero16();
; #pragma unroll
;       for (int ks = 0; ks < 4; ks++) {
;         bf16x8 a = *(const bf16x8*)&kdT[(w * 32 + r) * 72 + ks * 16 + hh];
;         bf16x8 bw = *(const bf16x8*)&WTl[(ni * 32 + r) * 72 + ks * 16 + hh];
;         pn = mfma16(a, bw, pn);
;       }
; #pragma unroll
;       for (int e = 0; e < 16; e++) PNT[(w * 32 + rowmap(e, lane)) * 136 + ni * 32 + r] = f2bf(-pn[e]);
;     }
	v_mfma_f32_32x32x16_bf16 a[16:31], v[20:23], v[0:3], a[16:31]
	ds_read_b128 v[0:3], v252 offset:18528
	s_waitcnt lgkmcnt(0)
	v_mfma_f32_32x32x16_bf16 a[0:15], v[20:23], v[0:3], a[0:15]
	v_accvgpr_read_b32 v1, a64
	s_nop 7
	v_accvgpr_read_b32 v0, a16
	v_cvt_pk_bf16_f32 v0, v0, s0
	ds_write_b16 v1, v0
	v_accvgpr_read_b32 v1, a65
	v_accvgpr_read_b32 v0, a0
	v_cvt_pk_bf16_f32 v0, v0, s0
	ds_write_b16 v1, v0
	v_accvgpr_read_b32 v0, a17
	v_cvt_pk_bf16_f32 v0, v0, s0
	v_accvgpr_read_b32 v1, a66
	ds_write_b16 v1, v0
	v_accvgpr_read_b32 v0, a1
	v_cvt_pk_bf16_f32 v0, v0, s0
	v_accvgpr_read_b32 v1, a67
	ds_write_b16 v1, v0
	v_accvgpr_read_b32 v0, a18
	v_cvt_pk_bf16_f32 v0, v0, s0
	v_accvgpr_read_b32 v1, a68
	ds_write_b16 v1, v0
	v_accvgpr_read_b32 v0, a2
	v_cvt_pk_bf16_f32 v0, v0, s0
	v_accvgpr_read_b32 v1, a69
	ds_write_b16 v1, v0
	v_accvgpr_read_b32 v0, a19
	v_cvt_pk_bf16_f32 v0, v0, s0
	v_accvgpr_read_b32 v1, a70
	ds_write_b16 v1, v0
	v_accvgpr_read_b32 v0, a3
	v_cvt_pk_bf16_f32 v0, v0, s0
	v_accvgpr_read_b32 v1, a71
	ds_write_b16 v1, v0
	v_accvgpr_read_b32 v0, a20
	v_cvt_pk_bf16_f32 v0, v0, s0
	v_accvgpr_read_b32 v1, a72
	ds_write_b16 v1, v0
	v_accvgpr_read_b32 v0, a4
	v_cvt_pk_bf16_f32 v0, v0, s0
	v_accvgpr_read_b32 v1, a73
	ds_write_b16 v1, v0
	v_accvgpr_read_b32 v0, a21
	v_cvt_pk_bf16_f32 v0, v0, s0
	v_accvgpr_read_b32 v1, a74
	ds_write_b16 v1, v0
	v_accvgpr_read_b32 v0, a5
	v_cvt_pk_bf16_f32 v0, v0, s0
	v_accvgpr_read_b32 v1, a75
	ds_write_b16 v1, v0
	v_accvgpr_read_b32 v0, a22
	v_cvt_pk_bf16_f32 v0, v0, s0
	v_accvgpr_read_b32 v1, a76
	ds_write_b16 v1, v0
	v_accvgpr_read_b32 v0, a6
	v_cvt_pk_bf16_f32 v0, v0, s0
	v_accvgpr_read_b32 v1, a77
	ds_write_b16 v1, v0
	v_accvgpr_read_b32 v0, a23
	v_cvt_pk_bf16_f32 v0, v0, s0
	v_accvgpr_read_b32 v1, a78
	ds_write_b16 v1, v0
	v_accvgpr_read_b32 v0, a7
	v_cvt_pk_bf16_f32 v0, v0, s0
	v_accvgpr_read_b32 v1, a79
	ds_write_b16 v1, v0
	v_accvgpr_read_b32 v0, a24
	v_cvt_pk_bf16_f32 v0, v0, s0
	v_accvgpr_read_b32 v1, a80
	ds_write_b16 v1, v0
	v_accvgpr_read_b32 v0, a8
	v_cvt_pk_bf16_f32 v0, v0, s0
	v_accvgpr_read_b32 v1, a81
	ds_write_b16 v1, v0
	v_accvgpr_read_b32 v0, a25
	v_cvt_pk_bf16_f32 v0, v0, s0
	v_accvgpr_read_b32 v1, a82
	ds_write_b16 v1, v0
	v_accvgpr_read_b32 v0, a9
	v_cvt_pk_bf16_f32 v0, v0, s0
	v_accvgpr_read_b32 v1, a83
	ds_write_b16 v1, v0
	v_accvgpr_read_b32 v0, a26
	v_cvt_pk_bf16_f32 v0, v0, s0
	v_accvgpr_read_b32 v1, a84
	ds_write_b16 v1, v0
	v_accvgpr_read_b32 v0, a10
	v_cvt_pk_bf16_f32 v0, v0, s0
	v_accvgpr_read_b32 v1, a85
	ds_write_b16 v1, v0
	v_accvgpr_read_b32 v0, a27
	v_cvt_pk_bf16_f32 v0, v0, s0
	v_accvgpr_read_b32 v1, a86
	ds_write_b16 v1, v0
	v_accvgpr_read_b32 v0, a11
	v_cvt_pk_bf16_f32 v0, v0, s0
	v_accvgpr_read_b32 v1, a87
	ds_write_b16 v1, v0
	v_accvgpr_read_b32 v0, a28
	v_cvt_pk_bf16_f32 v0, v0, s0
	v_accvgpr_read_b32 v1, a88
	ds_write_b16 v1, v0
	v_accvgpr_read_b32 v0, a12
	v_cvt_pk_bf16_f32 v0, v0, s0
	v_accvgpr_read_b32 v1, a89
	ds_write_b16 v1, v0
	v_accvgpr_read_b32 v0, a29
	v_cvt_pk_bf16_f32 v0, v0, s0
	v_accvgpr_read_b32 v1, a90
	ds_write_b16 v1, v0
	v_accvgpr_read_b32 v0, a13
	v_cvt_pk_bf16_f32 v0, v0, s0
	v_accvgpr_read_b32 v1, a91
	ds_write_b16 v1, v0
	v_accvgpr_read_b32 v0, a30
	v_cvt_pk_bf16_f32 v0, v0, s0
	v_accvgpr_read_b32 v1, a92
	ds_write_b16 v1, v0
	v_accvgpr_read_b32 v0, a14
	v_cvt_pk_bf16_f32 v0, v0, s0
	v_accvgpr_read_b32 v1, a93
	ds_write_b16 v1, v0
	v_accvgpr_read_b32 v0, a31
	v_cvt_pk_bf16_f32 v0, v0, s0
	v_accvgpr_read_b32 v1, a94
	ds_write_b16 v1, v0
	v_accvgpr_read_b32 v0, a15
	v_cvt_pk_bf16_f32 v0, v0, s0
	v_accvgpr_read_b32 v1, a95
	ds_write_b16 v1, v0
	global_load_dwordx4 a[196:199], v[10:11], off
	global_load_dwordx4 a[200:203], v[8:9], off
	global_load_dwordx4 a[204:207], v[6:7], off
	global_load_dwordx4 a[208:211], v[4:5], off
	ds_read_b128 v[0:3], v226
	ds_read_b128 v[12:15], v229 offset:18432
	s_waitcnt lgkmcnt(0)
	v_mfma_f32_32x32x16_bf16 a[0:15], v[0:3], v[12:15], 0
	ds_read_b128 v[12:15], v226 offset:32
	ds_read_b128 v[16:19], v229 offset:18464
	s_waitcnt lgkmcnt(0)
	v_mfma_f32_32x32x16_bf16 a[0:15], v[12:15], v[16:19], a[0:15]
	ds_read_b128 v[16:19], v226 offset:64
	ds_read_b128 v[20:23], v229 offset:18496
	s_waitcnt lgkmcnt(0)
	v_mfma_f32_32x32x16_bf16 a[0:15], v[16:19], v[20:23], a[0:15]
	ds_read_b128 v[20:23], v226 offset:96
	ds_read_b128 v[24:27], v229 offset:18528
	s_waitcnt lgkmcnt(0)
	v_mfma_f32_32x32x16_bf16 a[0:15], v[20:23], v[24:27], a[0:15]
	s_nop 11
	v_accvgpr_read_b32 v24, a0
	v_cvt_pk_bf16_f32 v24, -v24, s0
	ds_write_b16 v227, v24
	v_accvgpr_read_b32 v24, a1
	v_cvt_pk_bf16_f32 v24, -v24, s0
	ds_write_b16 v227, v24 offset:272
	v_accvgpr_read_b32 v24, a2
	v_cvt_pk_bf16_f32 v24, -v24, s0
	ds_write_b16 v227, v24 offset:544
	v_accvgpr_read_b32 v24, a3
	v_cvt_pk_bf16_f32 v24, -v24, s0
	ds_write_b16 v227, v24 offset:816
	v_accvgpr_read_b32 v24, a4
	v_cvt_pk_bf16_f32 v24, -v24, s0
	ds_write_b16 v227, v24 offset:2176
	v_accvgpr_read_b32 v24, a5
	v_cvt_pk_bf16_f32 v24, -v24, s0
	ds_write_b16 v227, v24 offset:2448
	v_accvgpr_read_b32 v24, a6
	v_cvt_pk_bf16_f32 v24, -v24, s0
	ds_write_b16 v227, v24 offset:2720
	v_accvgpr_read_b32 v24, a7
	v_cvt_pk_bf16_f32 v24, -v24, s0
	ds_write_b16 v227, v24 offset:2992
	v_accvgpr_read_b32 v24, a8
	v_cvt_pk_bf16_f32 v24, -v24, s0
	ds_write_b16 v227, v24 offset:4352
	v_accvgpr_read_b32 v24, a9
	v_cvt_pk_bf16_f32 v24, -v24, s0
	ds_write_b16 v227, v24 offset:4624
	v_accvgpr_read_b32 v24, a10
	v_cvt_pk_bf16_f32 v24, -v24, s0
	ds_write_b16 v227, v24 offset:4896
	v_accvgpr_read_b32 v24, a11
	v_cvt_pk_bf16_f32 v24, -v24, s0
	ds_write_b16 v227, v24 offset:5168
	v_accvgpr_read_b32 v24, a12
	v_cvt_pk_bf16_f32 v24, -v24, s0
	ds_write_b16 v227, v24 offset:6528
	v_accvgpr_read_b32 v24, a13
	v_cvt_pk_bf16_f32 v24, -v24, s0
	ds_write_b16 v227, v24 offset:6800
	v_accvgpr_read_b32 v24, a14
	v_cvt_pk_bf16_f32 v24, -v24, s0
	ds_write_b16 v227, v24 offset:7072
	v_accvgpr_read_b32 v24, a15
	v_cvt_pk_bf16_f32 v24, -v24, s0
	ds_write_b16 v227, v24 offset:7344
	ds_read_b128 v[24:27], v229 offset:23040
	s_waitcnt lgkmcnt(0)
; __device__ __forceinline__ u16 f2bf(float f) { return (u16)(pack2(f, f) & 0xffffu); }
; __device__ __forceinline__ int rowmap(int e, int lane) { return (e & 3) + 8 * (e >> 2) + 4 * (lane >> 5); }
; __device__ __forceinline__ void gdn_chunk_item(const Params& p, int item, char* smem) {
;     ...
; #pragma unroll
;     for (int ni = 0; ni < 4; ni++) {
;       f32x16 pn = zero16();
; #pragma unroll
;       for (int ks = 0; ks < 4; ks++) {
;         bf16x8 a = *(const bf16x8*)&kdT[(w * 32 + r) * 72 + ks * 16 + hh];
;         bf16x8 bw = *(const bf16x8*)&WTl[(ni * 32 + r) * 72 + ks * 16 + hh];
;         pn = mfma16(a, bw, pn);
;       }
; #pragma unroll
;       for (int e = 0; e < 16; e++) PNT[(w * 32 + rowmap(e, lane)) * 136 + ni * 32 + r] = f2bf(-pn[e]);
;     }
;     if (tid < 128) ((float*)(ws + OFF_DVEC))[(size_t)ci * 128 + tid] = __expf(gl);
	v_mfma_f32_32x32x16_bf16 a[0:15], v[0:3], v[24:27], 0
	ds_read_b128 v[24:27], v229 offset:23072
	s_waitcnt lgkmcnt(0)
	v_mfma_f32_32x32x16_bf16 a[0:15], v[12:15], v[24:27], a[0:15]
	ds_read_b128 v[24:27], v229 offset:23104
	s_waitcnt lgkmcnt(0)
	v_mfma_f32_32x32x16_bf16 a[0:15], v[16:19], v[24:27], a[0:15]
	ds_read_b128 v[24:27], v229 offset:23136
	s_waitcnt lgkmcnt(0)
	v_mfma_f32_32x32x16_bf16 a[0:15], v[20:23], v[24:27], a[0:15]
	s_nop 11
	v_accvgpr_read_b32 v24, a0
	v_cvt_pk_bf16_f32 v24, -v24, s0
	ds_write_b16 v227, v24 offset:64
	v_accvgpr_read_b32 v24, a1
	v_cvt_pk_bf16_f32 v24, -v24, s0
	ds_write_b16 v227, v24 offset:336
	v_accvgpr_read_b32 v24, a2
	v_cvt_pk_bf16_f32 v24, -v24, s0
	ds_write_b16 v227, v24 offset:608
	v_accvgpr_read_b32 v24, a3
	v_cvt_pk_bf16_f32 v24, -v24, s0
	ds_write_b16 v227, v24 offset:880
	v_accvgpr_read_b32 v24, a4
	v_cvt_pk_bf16_f32 v24, -v24, s0
	ds_write_b16 v227, v24 offset:2240
	v_accvgpr_read_b32 v24, a5
	v_cvt_pk_bf16_f32 v24, -v24, s0
	ds_write_b16 v227, v24 offset:2512
	v_accvgpr_read_b32 v24, a6
	v_cvt_pk_bf16_f32 v24, -v24, s0
	ds_write_b16 v227, v24 offset:2784
	v_accvgpr_read_b32 v24, a7
	v_cvt_pk_bf16_f32 v24, -v24, s0
	ds_write_b16 v227, v24 offset:3056
	v_accvgpr_read_b32 v24, a8
	v_cvt_pk_bf16_f32 v24, -v24, s0
	ds_write_b16 v227, v24 offset:4416
	v_accvgpr_read_b32 v24, a9
	v_cvt_pk_bf16_f32 v24, -v24, s0
	ds_write_b16 v227, v24 offset:4688
	v_accvgpr_read_b32 v24, a10
	v_cvt_pk_bf16_f32 v24, -v24, s0
	ds_write_b16 v227, v24 offset:4960
	v_accvgpr_read_b32 v24, a11
	v_cvt_pk_bf16_f32 v24, -v24, s0
	ds_write_b16 v227, v24 offset:5232
	v_accvgpr_read_b32 v24, a12
	v_cvt_pk_bf16_f32 v24, -v24, s0
	ds_write_b16 v227, v24 offset:6592
	v_accvgpr_read_b32 v24, a13
	v_cvt_pk_bf16_f32 v24, -v24, s0
	ds_write_b16 v227, v24 offset:6864
	v_accvgpr_read_b32 v24, a14
	v_cvt_pk_bf16_f32 v24, -v24, s0
	ds_write_b16 v227, v24 offset:7136
	v_accvgpr_read_b32 v24, a15
	v_cvt_pk_bf16_f32 v24, -v24, s0
	ds_write_b16 v227, v24 offset:7408
	ds_read_b128 v[24:27], v229 offset:27648
	s_waitcnt lgkmcnt(0)
	v_mfma_f32_32x32x16_bf16 a[0:15], v[0:3], v[24:27], 0
	ds_read_b128 v[24:27], v229 offset:27680
	s_waitcnt lgkmcnt(0)
	v_mfma_f32_32x32x16_bf16 a[0:15], v[12:15], v[24:27], a[0:15]
	ds_read_b128 v[24:27], v229 offset:27712
	s_waitcnt lgkmcnt(0)
	v_mfma_f32_32x32x16_bf16 a[0:15], v[16:19], v[24:27], a[0:15]
	ds_read_b128 v[24:27], v229 offset:27744
	s_waitcnt lgkmcnt(0)
	v_mfma_f32_32x32x16_bf16 a[0:15], v[20:23], v[24:27], a[0:15]
	s_nop 11
	v_accvgpr_read_b32 v24, a0
	v_cvt_pk_bf16_f32 v24, -v24, s0
	ds_write_b16 v227, v24 offset:128
	v_accvgpr_read_b32 v24, a1
	v_cvt_pk_bf16_f32 v24, -v24, s0
	ds_write_b16 v227, v24 offset:400
	v_accvgpr_read_b32 v24, a2
	v_cvt_pk_bf16_f32 v24, -v24, s0
	ds_write_b16 v227, v24 offset:672
	v_accvgpr_read_b32 v24, a3
	v_cvt_pk_bf16_f32 v24, -v24, s0
	ds_write_b16 v227, v24 offset:944
	v_accvgpr_read_b32 v24, a4
	v_cvt_pk_bf16_f32 v24, -v24, s0
	ds_write_b16 v227, v24 offset:2304
	v_accvgpr_read_b32 v24, a5
	v_cvt_pk_bf16_f32 v24, -v24, s0
	ds_write_b16 v227, v24 offset:2576
	v_accvgpr_read_b32 v24, a6
	v_cvt_pk_bf16_f32 v24, -v24, s0
	ds_write_b16 v227, v24 offset:2848
	v_accvgpr_read_b32 v24, a7
	v_cvt_pk_bf16_f32 v24, -v24, s0
	ds_write_b16 v227, v24 offset:3120
	v_accvgpr_read_b32 v24, a8
	v_cvt_pk_bf16_f32 v24, -v24, s0
	ds_write_b16 v227, v24 offset:4480
	v_accvgpr_read_b32 v24, a9
	v_cvt_pk_bf16_f32 v24, -v24, s0
	ds_write_b16 v227, v24 offset:4752
	v_accvgpr_read_b32 v24, a10
	v_cvt_pk_bf16_f32 v24, -v24, s0
	ds_write_b16 v227, v24 offset:5024
	v_accvgpr_read_b32 v24, a11
	v_cvt_pk_bf16_f32 v24, -v24, s0
	ds_write_b16 v227, v24 offset:5296
	v_accvgpr_read_b32 v24, a12
	v_cvt_pk_bf16_f32 v24, -v24, s0
	ds_write_b16 v227, v24 offset:6656
	v_accvgpr_read_b32 v24, a13
	v_cvt_pk_bf16_f32 v24, -v24, s0
	ds_write_b16 v227, v24 offset:6928
	v_accvgpr_read_b32 v24, a14
	v_cvt_pk_bf16_f32 v24, -v24, s0
	ds_write_b16 v227, v24 offset:7200
	v_accvgpr_read_b32 v24, a15
	v_cvt_pk_bf16_f32 v24, -v24, s0
	ds_write_b16 v227, v24 offset:7472
	ds_read_b128 v[24:27], v229 offset:32256
	s_waitcnt lgkmcnt(0)
	v_mfma_f32_32x32x16_bf16 a[0:15], v[0:3], v[24:27], 0
	ds_read_b128 v[0:3], v229 offset:32288
	s_waitcnt lgkmcnt(0)
	v_mfma_f32_32x32x16_bf16 a[0:15], v[12:15], v[0:3], a[0:15]
	ds_read_b128 v[0:3], v229 offset:32320
	s_waitcnt lgkmcnt(0)
	v_mfma_f32_32x32x16_bf16 a[0:15], v[16:19], v[0:3], a[0:15]
	ds_read_b128 v[0:3], v229 offset:32352
	s_waitcnt lgkmcnt(0)
	v_mfma_f32_32x32x16_bf16 a[0:15], v[20:23], v[0:3], a[0:15]
	s_nop 11
	v_accvgpr_read_b32 v0, a0
	v_cvt_pk_bf16_f32 v0, -v0, s0
	ds_write_b16 v227, v0 offset:192
	v_accvgpr_read_b32 v0, a1
	v_cvt_pk_bf16_f32 v0, -v0, s0
	ds_write_b16 v227, v0 offset:464
	v_accvgpr_read_b32 v0, a2
	v_cvt_pk_bf16_f32 v0, -v0, s0
	ds_write_b16 v227, v0 offset:736
	v_accvgpr_read_b32 v0, a3
	v_cvt_pk_bf16_f32 v0, -v0, s0
	ds_write_b16 v227, v0 offset:1008
	v_accvgpr_read_b32 v0, a4
	v_cvt_pk_bf16_f32 v0, -v0, s0
	ds_write_b16 v227, v0 offset:2368
	v_accvgpr_read_b32 v0, a5
	v_cvt_pk_bf16_f32 v0, -v0, s0
	ds_write_b16 v227, v0 offset:2640
	v_accvgpr_read_b32 v0, a6
	v_cvt_pk_bf16_f32 v0, -v0, s0
	ds_write_b16 v227, v0 offset:2912
	v_accvgpr_read_b32 v0, a7
	v_cvt_pk_bf16_f32 v0, -v0, s0
	ds_write_b16 v227, v0 offset:3184
	v_accvgpr_read_b32 v0, a8
	v_cvt_pk_bf16_f32 v0, -v0, s0
	ds_write_b16 v227, v0 offset:4544
	v_accvgpr_read_b32 v0, a9
	v_cvt_pk_bf16_f32 v0, -v0, s0
	ds_write_b16 v227, v0 offset:4816
	v_accvgpr_read_b32 v0, a10
	v_cvt_pk_bf16_f32 v0, -v0, s0
	ds_write_b16 v227, v0 offset:5088
	v_accvgpr_read_b32 v0, a11
	v_cvt_pk_bf16_f32 v0, -v0, s0
	ds_write_b16 v227, v0 offset:5360
	v_accvgpr_read_b32 v0, a12
	v_cvt_pk_bf16_f32 v0, -v0, s0
	ds_write_b16 v227, v0 offset:6720
	v_accvgpr_read_b32 v0, a13
	v_cvt_pk_bf16_f32 v0, -v0, s0
	ds_write_b16 v227, v0 offset:6992
	v_accvgpr_read_b32 v0, a14
	v_cvt_pk_bf16_f32 v0, -v0, s0
	ds_write_b16 v227, v0 offset:7264
	v_accvgpr_read_b32 v0, a15
	v_cvt_pk_bf16_f32 v0, -v0, s0
	ds_write_b16 v227, v0 offset:7536
	s_waitcnt vmcnt(0)
	s_and_saveexec_b64 s[6:7], s[30:31]
	s_cbranch_execz .LBB0_797
	v_mul_f32_e32 v0, 0x3fb8aa3b, v235
	v_exp_f32_e32 v2, v0
	v_accvgpr_read_b32 v0, a112
	s_lshl_b64 s[0:1], s[0:1], 9
	v_accvgpr_read_b32 v1, a113
	v_lshl_add_u64 v[0:1], v[0:1], 0, s[0:1]
	global_store_dword v[0:1], v2, off
	s_branch .LBB0_797
